# v13 minus five XNACK-replay s_nop pads between the attention staging loads (4.1 note a)
# speedup vs baseline: 1.0124x; 1.0014x over previous
; __device__ __forceinline__ void finishSM(f32x16& p0, f32x16& p1, float alpha, float& l_reg, bf16x8& pa0, bf16x8& pa1, bf16x8& pa2, bf16x8& pa3) {
;     for (int r = 0; r < 16; ++r) p1[r] = __builtin_amdgcn_exp2f(p1[r]);
;     float ps = 0; for (int r = 0; r < 16; ++r) ps += p0[r]; for (int r = 0; r < 16; ++r) ps += p1[r];
;     { auto rr = __builtin_amdgcn_permlane32_swap(__float_as_uint(ps), __float_as_uint(ps), false, false);
;       ps = __uint_as_float(rr[0]) + __uint_as_float(rr[1]); }
;     l_reg = l_reg * alpha + ps;
;     ...
;     PK4(p0, 0, pa0); PK4(p0, 8, pa1); PK4(p1, 0, pa2); PK4(p1, 8, pa3);
;     ...
; }
; template <int KB, bool SK>
; __device__ __forceinline__ void qkt(f32x16& p0, f32x16& p1, const char* K_lds, const float* B_lds, int r32, int hi, const bf16x8* qr, bool act) {
;     if (SK && !act) { const float NEG = -__builtin_inff();
; #pragma unroll
;         for (int r = 0; r < 16; ++r) { p0[r] = NEG; p1[r] = NEG; } return; }
;     ...
;     p0 = f32x16{}; p1 = f32x16{};
;     ...
;     p0 = *(const f32x16*)(B_lds + KB * 64 + hi * 32); p1 = *(const f32x16*)(B_lds + KB * 64 + hi * 32 + 16);
;     ...
;     const char* kb[4];
; #pragma unroll
;     for (int dd = 0; dd < 4; ++dd) kb[dd] = K_lds + KB * SHM_K + KSWZ(r32, (dd * 16 + hi * 8) * 2);
; #pragma unroll
;     for (int d0 = 0; d0 < 8; ++d0) { const char* a = kb[d0 & 3] + (d0 >> 2) * 128;
;         bf16x8 b0 = *reinterpret_cast<const bf16x8*>(a);
;         bf16x8 b1 = *reinterpret_cast<const bf16x8*>(a + 32 * 256);
;         p0 = __builtin_amdgcn_mfma_f32_32x32x16_bf16(b0, qr[d0], p0, 0, 0, 0);
;         p1 = __builtin_amdgcn_mfma_f32_32x32x16_bf16(b1, qr[d0], p1, 0, 0, 0); }
; }
; template <int VB, bool SK>
; __device__ __forceinline__ void pv_tile(f32x16* o, int vb0, bf16x8 pa0, bf16x8 pa1, bf16x8 pa2, bf16x8 pa3, bool act) {
;     if (SK && !act) return;
.LBB0_1247:
	v_add_u32_e32 v200, v230, v219
	v_add_u32_e32 v248, s68, v200
	v_add_u32_e32 v200, 1, v248
	v_lshl_add_u64 v[2:3], v[200:201], 2, s[66:67]
	v_mov_b32_e32 v15, v1
	v_add_u32_e32 v200, 0x10000, v14
	v_lshlrev_b64 v[10:11], 1, v[14:15]
	v_lshlrev_b64 v[12:13], 1, v[200:201]
	global_load_dword v246, v[2:3], off
	v_lshl_add_u64 v[2:3], s[64:65], 0, v[10:11]
	v_lshl_add_u64 v[6:7], s[64:65], 0, v[12:13]
	v_lshl_add_u64 v[10:11], s[62:63], 0, v[10:11]
	global_load_dwordx4 v[2:5], v[2:3], off
	global_load_dwordx4 v[6:9], v[6:7], off
	v_lshl_add_u64 v[210:211], s[62:63], 0, v[12:13]
	global_load_dwordx4 v[10:13], v[10:11], off
	global_load_dwordx4 v[210:213], v[210:211], off
	v_add_u32_e32 v0, 0x10900, v236
	ds_read_b128 v[100:103], v0
	ds_read_b128 v[104:107], v0 offset:16
	ds_read_b128 v[108:111], v0 offset:32
	s_waitcnt vmcnt(7)
	ds_read_b128 v[112:115], v0 offset:48
	ds_read_b128 v[96:99], v0 offset:112
	ds_read_b128 v[92:95], v0 offset:96
	ds_read_b128 v[88:91], v0 offset:80
	ds_read_b128 v[84:87], v0 offset:64
	ds_read_b128 v[202:205], v235 offset:49152
	ds_read_b128 v[206:209], v235 offset:57344
	v_add_f32_e32 v80, 0, v191
	v_add_f32_e32 v80, v193, v80
	v_add_f32_e32 v80, v189, v80
	s_waitcnt lgkmcnt(1)
	v_mfma_f32_32x32x16_bf16 v[100:115], v[202:205], v[172:175], v[100:115]
	v_add_f32_e32 v80, v192, v80
	v_add_f32_e32 v80, v188, v80
	v_add_f32_e32 v80, v190, v80
	v_add_f32_e32 v80, v186, v80
	v_add_f32_e32 v80, v187, v80
	v_add_f32_e32 v80, v182, v80
	v_add_f32_e32 v80, v185, v80
	s_waitcnt lgkmcnt(0)
	v_mfma_f32_32x32x16_bf16 v[84:99], v[206:209], v[172:175], v[84:99]
	ds_read_b128 v[202:205], v234 offset:49152
	ds_read_b128 v[206:209], v234 offset:57344
	v_add_f32_e32 v80, v179, v80
	v_add_f32_e32 v80, v183, v80
	v_exp_f32_e32 v0, v142
	v_add_f32_e32 v80, v177, v80
	v_add_f32_e32 v80, v184, v80
	v_add_f32_e32 v80, v178, v80
	s_waitcnt lgkmcnt(1)
	v_mfma_f32_32x32x16_bf16 v[100:115], v[202:205], v[168:171], v[100:115]
	v_add_f32_e32 v80, v181, v80
	v_add_f32_e32 v80, v0, v80
	v_exp_f32_e32 v194, v135
	v_exp_f32_e32 v195, v132
	v_exp_f32_e32 v196, v133
	v_exp_f32_e32 v197, v130
	v_exp_f32_e32 v198, v131
	s_waitcnt lgkmcnt(0)
	v_mfma_f32_32x32x16_bf16 v[84:99], v[206:209], v[168:171], v[84:99]
	ds_read_b128 v[202:205], v233 offset:49152
	ds_read_b128 v[206:209], v233 offset:57344
	v_exp_f32_e32 v127, v128
	v_exp_f32_e32 v128, v129
	s_sub_i32 s4, s68, 63
	s_waitcnt lgkmcnt(1)
	v_mfma_f32_32x32x16_bf16 v[100:115], v[202:205], v[164:167], v[100:115]
	s_waitcnt lgkmcnt(0)
	v_mfma_f32_32x32x16_bf16 v[84:99], v[206:209], v[164:167], v[84:99]
	ds_read_b128 v[202:205], v232 offset:49152
	ds_read_b128 v[206:209], v232 offset:57344
	s_waitcnt lgkmcnt(1)
	v_mfma_f32_32x32x16_bf16 v[100:115], v[202:205], v[160:163], v[100:115]
	s_waitcnt lgkmcnt(0)
	v_mfma_f32_32x32x16_bf16 v[84:99], v[206:209], v[160:163], v[84:99]
	ds_read_b128 v[202:205], v235 offset:49280
	ds_read_b128 v[206:209], v235 offset:57472
	s_waitcnt lgkmcnt(1)
	v_mfma_f32_32x32x16_bf16 v[100:115], v[202:205], v[156:159], v[100:115]
	s_waitcnt lgkmcnt(0)
	v_mfma_f32_32x32x16_bf16 v[84:99], v[206:209], v[156:159], v[84:99]
	ds_read_b128 v[202:205], v234 offset:49280
	ds_read_b128 v[206:209], v234 offset:57472
	s_waitcnt lgkmcnt(1)
	v_mfma_f32_32x32x16_bf16 v[100:115], v[202:205], v[152:155], v[100:115]
	s_waitcnt lgkmcnt(0)
	v_mfma_f32_32x32x16_bf16 v[84:99], v[206:209], v[152:155], v[84:99]
	ds_read_b128 v[202:205], v233 offset:49280
	ds_read_b128 v[206:209], v233 offset:57472
	s_waitcnt lgkmcnt(1)
	v_mfma_f32_32x32x16_bf16 v[100:115], v[202:205], v[148:151], v[100:115]
	s_waitcnt lgkmcnt(0)
	v_mfma_f32_32x32x16_bf16 v[84:99], v[206:209], v[148:151], v[84:99]
	ds_read_b128 v[202:205], v232 offset:49280
	ds_read_b128 v[206:209], v232 offset:57472
	s_waitcnt lgkmcnt(1)
	v_mfma_f32_32x32x16_bf16 v[100:115], v[202:205], v[144:147], v[100:115]
	v_exp_f32_e32 v202, v143
	v_exp_f32_e32 v203, v140
	v_exp_f32_e32 v204, v141
	v_exp_f32_e32 v205, v138
	v_add_f32_e32 v80, v202, v80
	v_add_f32_e32 v80, v203, v80
	v_add_f32_e32 v80, v204, v80
	s_waitcnt lgkmcnt(0)
	v_mfma_f32_32x32x16_bf16 v[84:99], v[206:209], v[144:147], v[84:99]
	v_exp_f32_e32 v206, v139
	v_exp_f32_e32 v207, v136
	v_exp_f32_e32 v208, v137
	v_exp_f32_e32 v209, v134
	v_add_f32_e32 v80, v205, v80
	v_add_f32_e32 v80, v206, v80
	v_add_f32_e32 v80, v207, v80
	v_add_f32_e32 v80, v208, v80
	v_add_f32_e32 v80, v209, v80
	v_add_f32_e32 v80, v194, v80
	v_add_f32_e32 v80, v195, v80
	v_add_f32_e32 v80, v196, v80
	v_add_f32_e32 v80, v197, v80
	v_add_f32_e32 v80, v198, v80
	v_add_f32_e32 v80, v127, v80
	v_add_f32_e32 v244, v128, v80
	v_mov_b32_e32 v245, v244
	s_nop 1
	v_permlane32_swap_b32_e32 v244, v245
	v_cvt_pk_bf16_f32 v80, v191, v193
	v_cvt_pk_bf16_f32 v81, v189, v192
	v_cvt_pk_bf16_f32 v82, v188, v190
	v_cvt_pk_bf16_f32 v83, v186, v187
	s_waitcnt vmcnt(6)
	v_cvt_pk_bf16_f32 v116, v182, v185
	v_cvt_pk_bf16_f32 v117, v179, v183
	v_cvt_pk_bf16_f32 v118, v177, v184
	v_cvt_pk_bf16_f32 v119, v178, v181
	s_waitcnt vmcnt(5)
	v_cvt_pk_bf16_f32 v120, v0, v202
	v_cvt_pk_bf16_f32 v121, v203, v204
	v_cvt_pk_bf16_f32 v122, v205, v206
	v_cvt_pk_bf16_f32 v123, v207, v208
	v_cvt_pk_bf16_f32 v124, v209, v194
	v_cvt_pk_bf16_f32 v125, v195, v196
	v_cvt_pk_bf16_f32 v126, v197, v198
	v_cvt_pk_bf16_f32 v127, v127, v128
	v_permlane32_swap_b32_e32 v80, v82
	v_permlane32_swap_b32_e32 v81, v83
	v_permlane32_swap_b32_e32 v116, v118
	v_permlane32_swap_b32_e32 v117, v119
	v_permlane32_swap_b32_e32 v120, v122
	v_permlane32_swap_b32_e32 v121, v123
	v_permlane32_swap_b32_e32 v124, v126
	v_permlane32_swap_b32_e32 v125, v127
	ds_read_b64_tr_b16 v[128:129], v227 offset:0
	ds_read_b64_tr_b16 v[130:131], v227 offset:0x800
	ds_read_b64_tr_b16 v[132:133], v227 offset:0x1000
	ds_read_b64_tr_b16 v[134:135], v227 offset:0x1800
	ds_read_b64_tr_b16 v[136:137], v227 offset:0x2000
	ds_read_b64_tr_b16 v[138:139], v227 offset:0x2800
	ds_read_b64_tr_b16 v[140:141], v227 offset:0x3000
	ds_read_b64_tr_b16 v[142:143], v227 offset:0x3800
	s_waitcnt lgkmcnt(0)
; template <int VB, bool SK>
; __device__ __forceinline__ void pv_tile(f32x16* o, int vb0, bf16x8 pa0, bf16x8 pa1, bf16x8 pa2, bf16x8 pa3, bool act) {
;     if (SK && !act) return;
;     ...
;     PV_D0(0); PV_D0(1); PV_D0(2); PV_D0(3);
	s_nop 0
	v_mfma_f32_32x32x16_bf16 v[64:79], v[80:83], v[128:131], v[64:79]
	ds_read_b64_tr_b16 v[128:129], v227 offset:0x200
	ds_read_b64_tr_b16 v[130:131], v227 offset:0xa00
	v_mfma_f32_32x32x16_bf16 v[64:79], v[116:119], v[132:135], v[64:79]
	ds_read_b64_tr_b16 v[132:133], v227 offset:0x1200
	ds_read_b64_tr_b16 v[134:135], v227 offset:0x1a00
	v_mfma_f32_32x32x16_bf16 v[64:79], v[120:123], v[136:139], v[64:79]
	ds_read_b64_tr_b16 v[136:137], v227 offset:0x2200
	ds_read_b64_tr_b16 v[138:139], v227 offset:0x2a00
	v_mfma_f32_32x32x16_bf16 v[64:79], v[124:127], v[140:143], v[64:79]
	ds_read_b64_tr_b16 v[140:141], v227 offset:0x3200
	ds_read_b64_tr_b16 v[142:143], v227 offset:0x3a00
	s_waitcnt lgkmcnt(0)
	v_mfma_f32_32x32x16_bf16 v[48:63], v[80:83], v[128:131], v[48:63]
	ds_read_b64_tr_b16 v[128:129], v227 offset:0x400
	ds_read_b64_tr_b16 v[130:131], v227 offset:0xc00
	v_mfma_f32_32x32x16_bf16 v[48:63], v[116:119], v[132:135], v[48:63]
	ds_read_b64_tr_b16 v[132:133], v227 offset:0x1400
	ds_read_b64_tr_b16 v[134:135], v227 offset:0x1c00
	v_mfma_f32_32x32x16_bf16 v[48:63], v[120:123], v[136:139], v[48:63]
	ds_read_b64_tr_b16 v[136:137], v227 offset:0x2400
	ds_read_b64_tr_b16 v[138:139], v227 offset:0x2c00
	v_mfma_f32_32x32x16_bf16 v[48:63], v[124:127], v[140:143], v[48:63]
	ds_read_b64_tr_b16 v[140:141], v227 offset:0x3400
	ds_read_b64_tr_b16 v[142:143], v227 offset:0x3c00
	s_waitcnt lgkmcnt(0)
	v_mfma_f32_32x32x16_bf16 v[32:47], v[80:83], v[128:131], v[32:47]
	ds_read_b64_tr_b16 v[128:129], v227 offset:0x600
	ds_read_b64_tr_b16 v[130:131], v227 offset:0xe00
	v_mfma_f32_32x32x16_bf16 v[32:47], v[116:119], v[132:135], v[32:47]
	ds_read_b64_tr_b16 v[132:133], v227 offset:0x1600
	ds_read_b64_tr_b16 v[134:135], v227 offset:0x1e00
	v_mfma_f32_32x32x16_bf16 v[32:47], v[120:123], v[136:139], v[32:47]
	ds_read_b64_tr_b16 v[136:137], v227 offset:0x2600
	ds_read_b64_tr_b16 v[138:139], v227 offset:0x2e00
	v_mfma_f32_32x32x16_bf16 v[32:47], v[124:127], v[140:143], v[32:47]
	ds_read_b64_tr_b16 v[140:141], v227 offset:0x3600
	ds_read_b64_tr_b16 v[142:143], v227 offset:0x3e00
	s_waitcnt lgkmcnt(0)
	s_barrier
	s_waitcnt vmcnt(0)
	ds_write_b128 v237, v[2:5]
	ds_write_b128 v238, v[6:9]
	ds_write_b32 v242, v246
	ds_write_b128 v222, v[10:13] offset:32768
	ds_write_b128 v222, v[210:213] offset:40960
	v_mfma_f32_32x32x16_bf16 v[16:31], v[80:83], v[128:131], v[16:31]
	s_cmp_le_i32 s68, s57
	s_cselect_b64 s[28:29], -1, 0
	s_cmp_gt_i32 s4, s58
	s_cselect_b64 s[4:5], -1, 0
	s_and_b64 s[4:5], s[28:29], s[4:5]
	s_and_b64 vcc, exec, s[4:5]
	v_mfma_f32_32x32x16_bf16 v[16:31], v[116:119], v[132:135], v[16:31]
	v_mfma_f32_32x32x16_bf16 v[16:31], v[120:123], v[136:139], v[16:31]
	v_mfma_f32_32x32x16_bf16 v[16:31], v[124:127], v[140:143], v[16:31]
	s_cbranch_vccnz .LBB0_1249
	v_add_u32_e32 v0, 0x107b, v243
	v_cmp_gt_u32_e32 vcc, s81, v0
	v_add_u32_e32 v0, 0x5b, v243
	s_nop 0
	v_cndmask_b32_e32 v100, v216, v100, vcc
	v_cmp_lt_u32_e32 vcc, s82, v0
	v_add_u32_e32 v0, 0x7a, v243
	s_nop 0
	v_cndmask_b32_e32 v84, v216, v84, vcc
	v_cmp_lt_u32_e32 vcc, s82, v0
	v_add_u32_e32 v0, 0x5a, v243
	s_nop 0
	v_cndmask_b32_e32 v101, v216, v101, vcc
	v_cmp_lt_u32_e32 vcc, s82, v0
	v_add_u32_e32 v0, 0x79, v243
	s_nop 0
	v_cndmask_b32_e32 v85, v216, v85, vcc
	v_cmp_lt_u32_e32 vcc, s82, v0
	v_add_u32_e32 v0, 0x59, v243
	s_nop 0
	v_cndmask_b32_e32 v102, v216, v102, vcc
	v_cmp_lt_u32_e32 vcc, s82, v0
	v_add_u32_e32 v0, 0x78, v243
	s_nop 0
	v_cndmask_b32_e32 v86, v216, v86, vcc
	v_cmp_lt_u32_e32 vcc, s82, v0
	v_add_u32_e32 v0, 0x58, v243
	s_nop 0
	v_cndmask_b32_e32 v103, v216, v103, vcc
	v_cmp_lt_u32_e32 vcc, s82, v0
	v_add_u32_e32 v0, 0x73, v243
	s_nop 0
	v_cndmask_b32_e32 v87, v216, v87, vcc
	v_cmp_lt_u32_e32 vcc, s82, v0
	v_add_u32_e32 v0, 0x53, v243
	s_nop 0
	v_cndmask_b32_e32 v104, v216, v104, vcc
	v_cmp_lt_u32_e32 vcc, s82, v0
	v_add_u32_e32 v0, 0x72, v243
	s_nop 0
	v_cndmask_b32_e32 v88, v216, v88, vcc
	v_cmp_lt_u32_e32 vcc, s82, v0
	v_add_u32_e32 v0, 0x52, v243
	s_nop 0
	v_cndmask_b32_e32 v105, v216, v105, vcc
	v_cmp_lt_u32_e32 vcc, s82, v0
	v_add_u32_e32 v0, 0x71, v243
	s_nop 0
	v_cndmask_b32_e32 v89, v216, v89, vcc
	v_cmp_lt_u32_e32 vcc, s82, v0
	v_add_u32_e32 v0, 0x51, v243
	s_nop 0
	v_cndmask_b32_e32 v106, v216, v106, vcc
	v_cmp_lt_u32_e32 vcc, s82, v0
	v_add_u32_e32 v0, 0x70, v243
	s_nop 0
	v_cndmask_b32_e32 v90, v216, v90, vcc
	v_cmp_lt_u32_e32 vcc, s82, v0
	v_add_u32_e32 v0, 0x50, v243
	s_nop 0
	v_cndmask_b32_e32 v107, v216, v107, vcc
	v_cmp_lt_u32_e32 vcc, s82, v0
	v_add_u32_e32 v0, 0x6b, v243
	s_nop 0
	v_cndmask_b32_e32 v91, v216, v91, vcc
	v_cmp_lt_u32_e32 vcc, s82, v0
	v_add_u32_e32 v0, 0x4b, v243
	s_nop 0
	v_cndmask_b32_e32 v108, v216, v108, vcc
	v_cmp_lt_u32_e32 vcc, s82, v0
	v_add_u32_e32 v0, 0x6a, v243
	s_nop 0
	v_cndmask_b32_e32 v92, v216, v92, vcc
	v_cmp_lt_u32_e32 vcc, s82, v0
	v_add_u32_e32 v0, 0x4a, v243
	s_nop 0
	v_cndmask_b32_e32 v109, v216, v109, vcc
	v_cmp_lt_u32_e32 vcc, s82, v0
	v_add_u32_e32 v0, 0x69, v243
	s_nop 0
	v_cndmask_b32_e32 v93, v216, v93, vcc
	v_cmp_lt_u32_e32 vcc, s82, v0
	v_add_u32_e32 v0, 0x49, v243
	s_nop 0
	v_cndmask_b32_e32 v110, v216, v110, vcc
	v_cmp_lt_u32_e32 vcc, s82, v0
	v_add_u32_e32 v0, 0x68, v243
	s_nop 0
	v_cndmask_b32_e32 v94, v216, v94, vcc
	v_cmp_lt_u32_e32 vcc, s82, v0
	v_add_u32_e32 v0, 0x48, v243
	s_nop 0
	v_cndmask_b32_e32 v111, v216, v111, vcc
	v_cmp_lt_u32_e32 vcc, s82, v0
	v_add_u32_e32 v0, 0x63, v243
	s_nop 0
	v_cndmask_b32_e32 v95, v216, v95, vcc
	v_cmp_lt_u32_e32 vcc, s82, v0
	v_add_u32_e32 v0, 0x43, v243
	s_nop 0
	v_cndmask_b32_e32 v112, v216, v112, vcc
	v_cmp_lt_u32_e32 vcc, s82, v0
	v_add_u32_e32 v0, 0x62, v243
	s_nop 0
	v_cndmask_b32_e32 v96, v216, v96, vcc
	v_cmp_lt_u32_e32 vcc, s82, v0
	v_add_u32_e32 v0, 0x42, v243
	s_nop 0
	v_cndmask_b32_e32 v113, v216, v113, vcc
	v_cmp_lt_u32_e32 vcc, s82, v0
	v_add_u32_e32 v0, 0x61, v243
	s_nop 0
	v_cndmask_b32_e32 v97, v216, v97, vcc
	v_cmp_lt_u32_e32 vcc, s82, v0
	v_add_u32_e32 v0, 0x41, v243
	s_nop 0
	v_cndmask_b32_e32 v114, v216, v114, vcc
	v_cmp_lt_u32_e32 vcc, s82, v0
	v_add_u32_e32 v0, 0x60, v243
	s_nop 0
	v_cndmask_b32_e32 v98, v216, v98, vcc
	v_cmp_lt_u32_e32 vcc, s82, v0
	v_add_u32_e32 v0, 64, v243
	s_nop 0
	v_cndmask_b32_e32 v115, v216, v115, vcc
	v_cmp_lt_u32_e32 vcc, s82, v0
	s_nop 1
	v_cndmask_b32_e32 v99, v216, v99, vcc

; __device__ __forceinline__ void partialSM(f32x16& p0, f32x16& p1, float& m_reg, float& mn, float& alpha) {
;     ...
;     constexpr float C2 = 1.4426950408889634f * SCALE;
;     if (__builtin_expect(__all((pmax - m_reg) * SCALE <= THR), 1)) { mn = m_reg; alpha = 1.f; }
;     else { mn = fmaxf(m_reg, pmax); alpha = __builtin_amdgcn_exp2f((m_reg - mn) * C2); m_reg = mn; }
;     const float mnL = -mn * C2;
;     for (int r = 0; r < 16; ++r) p0[r] = fmaf(p0[r], C2, mnL); for (int r = 0; r < 16; ++r) p1[r] = fmaf(p1[r], C2, mnL);
;     for (int r = 0; r < 16; ++r) p0[r] = __builtin_amdgcn_exp2f(p0[r]);
.LBB0_1253:
	s_waitcnt lgkmcnt(0)
	s_barrier
	v_cndmask_b32_e64 v247, v0, v180, s[4:5]
	v_mul_f32_e32 v0, 0xbe0293ee, v247
	v_fmamk_f32 v80, v100, 0x3e0293ee, v0
	v_fmamk_f32 v81, v101, 0x3e0293ee, v0
	v_fmamk_f32 v82, v102, 0x3e0293ee, v0
	v_fmamk_f32 v83, v103, 0x3e0293ee, v0
	v_fmamk_f32 v116, v104, 0x3e0293ee, v0
	v_fmamk_f32 v117, v105, 0x3e0293ee, v0
	v_fmamk_f32 v118, v106, 0x3e0293ee, v0
	v_fmamk_f32 v119, v107, 0x3e0293ee, v0
	v_fmamk_f32 v120, v108, 0x3e0293ee, v0
	v_fmamk_f32 v121, v109, 0x3e0293ee, v0
	v_fmamk_f32 v122, v110, 0x3e0293ee, v0
	v_fmamk_f32 v123, v111, 0x3e0293ee, v0
	v_fmamk_f32 v112, v112, 0x3e0293ee, v0
	v_fmamk_f32 v113, v113, 0x3e0293ee, v0
	v_fmamk_f32 v114, v114, 0x3e0293ee, v0
	v_fmamk_f32 v115, v115, 0x3e0293ee, v0
	v_fmamk_f32 v100, v84, 0x3e0293ee, v0
	v_fmamk_f32 v109, v85, 0x3e0293ee, v0
	v_fmamk_f32 v110, v86, 0x3e0293ee, v0
	v_fmamk_f32 v111, v87, 0x3e0293ee, v0
	v_fmamk_f32 v180, v88, 0x3e0293ee, v0
	v_fmamk_f32 v101, v89, 0x3e0293ee, v0
	v_fmamk_f32 v102, v90, 0x3e0293ee, v0
	v_fmamk_f32 v103, v91, 0x3e0293ee, v0
	v_fmamk_f32 v104, v92, 0x3e0293ee, v0
	v_fmamk_f32 v105, v93, 0x3e0293ee, v0
	v_fmamk_f32 v106, v94, 0x3e0293ee, v0
	v_fmamk_f32 v107, v95, 0x3e0293ee, v0
	v_exp_f32_e32 v80, v80
	v_exp_f32_e32 v81, v81
	v_exp_f32_e32 v82, v82
	v_exp_f32_e32 v83, v83
	v_exp_f32_e32 v84, v116
	v_exp_f32_e32 v85, v117
	v_exp_f32_e32 v86, v118
	v_exp_f32_e32 v87, v119
	v_exp_f32_e32 v88, v120
	v_exp_f32_e32 v89, v121
	v_exp_f32_e32 v90, v122
	v_exp_f32_e32 v91, v123
	v_exp_f32_e32 v92, v112
	v_exp_f32_e32 v93, v113
	v_exp_f32_e32 v94, v114
	v_exp_f32_e32 v95, v115
	v_fmamk_f32 v108, v96, 0x3e0293ee, v0
	v_fmamk_f32 v181, v97, 0x3e0293ee, v0
	v_fmamk_f32 v182, v98, 0x3e0293ee, v0
	v_fmac_f32_e32 v0, 0x3e0293ee, v99
	s_add_i32 s4, s61, 1
	s_cmp_lt_i32 s4, s59
	s_cselect_b64 s[28:29], -1, 0
	s_cmp_ge_i32 s4, s59
	s_cbranch_scc1 .Lattn_h2_noload
	v_add_u32_e32 v200, 0x41, v248
	v_lshl_add_u64 v[2:3], v[200:201], 2, s[66:67]
	v_add_u32_e32 v200, 0x20000, v14
	v_lshlrev_b64 v[10:11], 1, v[200:201]
	v_add_u32_e32 v200, 0x30000, v14
	v_lshlrev_b64 v[12:13], 1, v[200:201]
	global_load_dword v246, v[2:3], off
	v_lshl_add_u64 v[2:3], s[64:65], 0, v[10:11]
	v_lshl_add_u64 v[6:7], s[64:65], 0, v[12:13]
	v_lshl_add_u64 v[10:11], s[62:63], 0, v[10:11]
	v_lshl_add_u64 v[176:177], s[62:63], 0, v[12:13]
	global_load_dwordx4 v[2:5], v[2:3], off
	global_load_dwordx4 v[6:9], v[6:7], off
	global_load_dwordx4 v[10:13], v[10:11], off
	global_load_dwordx4 v[176:179], v[176:177], off
